# RWKV scan chunk body re-emitted: LDS reads of next step fill DPP hazard slots, deferred y finalisation; plus XCD-affine attention queue and scalar-base staging
# speedup vs baseline: 1.0413x; 1.0304x over previous
.LBB0_65:
	s_bitcmp1_b32 s40, 0
	s_cselect_b32 s2, 0x5500, 0
	v_lshl_or_b32 v94, v93, 2, s2
	v_lshl_add_u32 v95, v0, 2, s2
	v_mov_b32_e32 v96, s2
	v_mul_u32_u24_e32 v46, 0x154, v93
	v_add_u32_e32 v47, v46, v96
	v_add_u32_e32 v46, v46, v95
	ds_read_b64 v[44:45], v47 offset:1344
	ds_read_b32 v48, v46 offset:1280
	ds_read_b128 v[110:113], v94
	ds_read_b128 v[126:129], v94 offset:1024
	ds_read_b128 v[114:117], v94 offset:256
	ds_read_b128 v[118:121], v94 offset:512
	ds_read_b128 v[122:125], v94 offset:768
	ds_read_b32 v130, v95 offset:1280
	s_mov_b64 s[2:3], 0x100
	s_mov_b64 s[20:21], 0x800
	s_waitcnt lgkmcnt(4)
	v_pk_mul_f32 v[24:25], v[30:31], v[112:113]
	v_pk_mul_f32 v[26:27], v[30:31], v[128:129]
	v_pk_fma_f32 v[24:25], v[28:29], v[110:111], v[24:25]
	v_pk_fma_f32 v[26:27], v[28:29], v[126:127], v[26:27]
	ds_read_b128 v[134:137], v94 offset:1360
	v_add_f32_e32 v34, v24, v25
	v_add_f32_e32 v35, v26, v27
	ds_read_b128 v[150:153], v94 offset:2384
	v_add_f32_dpp v34, v34, v34 quad_perm:[1,0,3,2] row_mask:0xf bank_mask:0xf bound_ctrl:1
	v_add_f32_dpp v35, v35, v35 quad_perm:[1,0,3,2] row_mask:0xf bank_mask:0xf bound_ctrl:1
	ds_read_b128 v[138:141], v94 offset:1616
	v_add_f32_dpp v34, v34, v34 quad_perm:[2,3,0,1] row_mask:0xf bank_mask:0xf bound_ctrl:1
	v_add_f32_dpp v35, v35, v35 quad_perm:[2,3,0,1] row_mask:0xf bank_mask:0xf bound_ctrl:1
	ds_read_b128 v[142:145], v94 offset:1872
	v_add_f32_dpp v34, v34, v34 row_ror:4 row_mask:0xf bank_mask:0xf bound_ctrl:1
	v_add_f32_dpp v35, v35, v35 row_ror:4 row_mask:0xf bank_mask:0xf bound_ctrl:1
	ds_read_b128 v[146:149], v94 offset:2128
	v_add_f32_dpp v34, v34, v34 row_ror:8 row_mask:0xf bank_mask:0xf bound_ctrl:1
	v_add_f32_dpp v35, v35, v35 row_ror:8 row_mask:0xf bank_mask:0xf bound_ctrl:1
	s_waitcnt lgkmcnt(5)
	v_pk_mul_f32 v[36:37], v[114:115], v[34:35] op_sel_hi:[1,0]
	v_pk_mul_f32 v[38:39], v[116:117], v[34:35] op_sel_hi:[1,0]
	v_pk_fma_f32 v[36:37], v[122:123], v[130:131], v[36:37] op_sel_hi:[1,0,1] neg_lo:[0,0,1] neg_hi:[0,0,1]
	v_pk_fma_f32 v[38:39], v[124:125], v[130:131], v[38:39] op_sel_hi:[1,0,1] neg_lo:[0,0,1] neg_hi:[0,0,1]
	v_cndmask_b32_e64 v42, 0, v34, s[30:31]
	v_pk_fma_f32 v[28:29], v[28:29], v[118:119], v[36:37]
	v_pk_fma_f32 v[30:31], v[30:31], v[120:121], v[38:39]
	v_cndmask_b32_e64 v43, 0, v35, s[30:31]
	ds_read_b32 v154, v95 offset:2640
	s_waitcnt lgkmcnt(4)
	v_pk_mul_f32 v[24:25], v[30:31], v[136:137]
	v_pk_mul_f32 v[26:27], v[30:31], v[152:153]
	v_pk_fma_f32 v[24:25], v[28:29], v[134:135], v[24:25]
	v_pk_fma_f32 v[26:27], v[28:29], v[150:151], v[26:27]
	ds_read_b128 v[110:113], v94 offset:2720
	v_add_f32_e32 v34, v24, v25
	v_add_f32_e32 v35, v26, v27
	ds_read_b128 v[126:129], v94 offset:3744
	v_add_f32_dpp v34, v34, v34 quad_perm:[1,0,3,2] row_mask:0xf bank_mask:0xf bound_ctrl:1
	v_add_f32_dpp v35, v35, v35 quad_perm:[1,0,3,2] row_mask:0xf bank_mask:0xf bound_ctrl:1
	ds_read_b128 v[114:117], v94 offset:2976
	v_add_f32_dpp v34, v34, v34 quad_perm:[2,3,0,1] row_mask:0xf bank_mask:0xf bound_ctrl:1
	v_add_f32_dpp v35, v35, v35 quad_perm:[2,3,0,1] row_mask:0xf bank_mask:0xf bound_ctrl:1
	ds_read_b128 v[118:121], v94 offset:3232
	v_add_f32_dpp v34, v34, v34 row_ror:4 row_mask:0xf bank_mask:0xf bound_ctrl:1
	v_add_f32_dpp v35, v35, v35 row_ror:4 row_mask:0xf bank_mask:0xf bound_ctrl:1
	ds_read_b128 v[122:125], v94 offset:3488
	v_add_f32_dpp v34, v34, v34 row_ror:8 row_mask:0xf bank_mask:0xf bound_ctrl:1
	v_add_f32_dpp v35, v35, v35 row_ror:8 row_mask:0xf bank_mask:0xf bound_ctrl:1
	s_waitcnt lgkmcnt(5)
	v_pk_mul_f32 v[36:37], v[138:139], v[34:35] op_sel_hi:[1,0]
	v_pk_mul_f32 v[38:39], v[140:141], v[34:35] op_sel_hi:[1,0]
	v_pk_fma_f32 v[36:37], v[146:147], v[154:155], v[36:37] op_sel_hi:[1,0,1] neg_lo:[0,0,1] neg_hi:[0,0,1]
	v_pk_fma_f32 v[38:39], v[148:149], v[154:155], v[38:39] op_sel_hi:[1,0,1] neg_lo:[0,0,1] neg_hi:[0,0,1]
	v_cndmask_b32_e64 v42, v42, v34, s[70:71]
	v_pk_fma_f32 v[28:29], v[28:29], v[142:143], v[36:37]
	v_pk_fma_f32 v[30:31], v[30:31], v[144:145], v[38:39]
	v_cndmask_b32_e64 v43, v43, v35, s[70:71]
	ds_read_b32 v130, v95 offset:4000
	s_waitcnt lgkmcnt(4)
	v_pk_mul_f32 v[24:25], v[30:31], v[112:113]
	v_pk_mul_f32 v[26:27], v[30:31], v[128:129]
	v_pk_fma_f32 v[24:25], v[28:29], v[110:111], v[24:25]
	v_pk_fma_f32 v[26:27], v[28:29], v[126:127], v[26:27]
	ds_read_b128 v[134:137], v94 offset:4080
	v_add_f32_e32 v34, v24, v25
	v_add_f32_e32 v35, v26, v27
	ds_read_b128 v[150:153], v94 offset:5104
	v_add_f32_dpp v34, v34, v34 quad_perm:[1,0,3,2] row_mask:0xf bank_mask:0xf bound_ctrl:1
	v_add_f32_dpp v35, v35, v35 quad_perm:[1,0,3,2] row_mask:0xf bank_mask:0xf bound_ctrl:1
	ds_read_b128 v[138:141], v94 offset:4336
	v_add_f32_dpp v34, v34, v34 quad_perm:[2,3,0,1] row_mask:0xf bank_mask:0xf bound_ctrl:1
	v_add_f32_dpp v35, v35, v35 quad_perm:[2,3,0,1] row_mask:0xf bank_mask:0xf bound_ctrl:1
	ds_read_b128 v[142:145], v94 offset:4592
	v_add_f32_dpp v34, v34, v34 row_ror:4 row_mask:0xf bank_mask:0xf bound_ctrl:1
	v_add_f32_dpp v35, v35, v35 row_ror:4 row_mask:0xf bank_mask:0xf bound_ctrl:1
	ds_read_b128 v[146:149], v94 offset:4848
	v_add_f32_dpp v34, v34, v34 row_ror:8 row_mask:0xf bank_mask:0xf bound_ctrl:1
	v_add_f32_dpp v35, v35, v35 row_ror:8 row_mask:0xf bank_mask:0xf bound_ctrl:1
	s_waitcnt lgkmcnt(5)
	v_pk_mul_f32 v[36:37], v[114:115], v[34:35] op_sel_hi:[1,0]
	v_pk_mul_f32 v[38:39], v[116:117], v[34:35] op_sel_hi:[1,0]
	v_pk_fma_f32 v[36:37], v[122:123], v[130:131], v[36:37] op_sel_hi:[1,0,1] neg_lo:[0,0,1] neg_hi:[0,0,1]
	v_pk_fma_f32 v[38:39], v[124:125], v[130:131], v[38:39] op_sel_hi:[1,0,1] neg_lo:[0,0,1] neg_hi:[0,0,1]
	v_cndmask_b32_e64 v42, v42, v34, s[72:73]
	v_pk_fma_f32 v[28:29], v[28:29], v[118:119], v[36:37]
	v_pk_fma_f32 v[30:31], v[30:31], v[120:121], v[38:39]
	v_cndmask_b32_e64 v43, v43, v35, s[72:73]
	ds_read_b32 v154, v95 offset:5360
	s_waitcnt lgkmcnt(4)
	v_pk_mul_f32 v[24:25], v[30:31], v[136:137]
	v_pk_mul_f32 v[26:27], v[30:31], v[152:153]
	v_pk_fma_f32 v[24:25], v[28:29], v[134:135], v[24:25]
	v_pk_fma_f32 v[26:27], v[28:29], v[150:151], v[26:27]
	ds_read_b128 v[110:113], v94 offset:5440
	v_add_f32_e32 v34, v24, v25
	v_add_f32_e32 v35, v26, v27
	ds_read_b128 v[126:129], v94 offset:6464
	v_add_f32_dpp v34, v34, v34 quad_perm:[1,0,3,2] row_mask:0xf bank_mask:0xf bound_ctrl:1
	v_add_f32_dpp v35, v35, v35 quad_perm:[1,0,3,2] row_mask:0xf bank_mask:0xf bound_ctrl:1
	ds_read_b128 v[114:117], v94 offset:5696
	v_add_f32_dpp v34, v34, v34 quad_perm:[2,3,0,1] row_mask:0xf bank_mask:0xf bound_ctrl:1
	v_add_f32_dpp v35, v35, v35 quad_perm:[2,3,0,1] row_mask:0xf bank_mask:0xf bound_ctrl:1
	ds_read_b128 v[118:121], v94 offset:5952
	v_add_f32_dpp v34, v34, v34 row_ror:4 row_mask:0xf bank_mask:0xf bound_ctrl:1
	v_add_f32_dpp v35, v35, v35 row_ror:4 row_mask:0xf bank_mask:0xf bound_ctrl:1
	ds_read_b128 v[122:125], v94 offset:6208
	v_add_f32_dpp v34, v34, v34 row_ror:8 row_mask:0xf bank_mask:0xf bound_ctrl:1
	v_add_f32_dpp v35, v35, v35 row_ror:8 row_mask:0xf bank_mask:0xf bound_ctrl:1
	s_waitcnt lgkmcnt(5)
	v_pk_mul_f32 v[36:37], v[138:139], v[34:35] op_sel_hi:[1,0]
	v_pk_mul_f32 v[38:39], v[140:141], v[34:35] op_sel_hi:[1,0]
	v_pk_fma_f32 v[36:37], v[146:147], v[154:155], v[36:37] op_sel_hi:[1,0,1] neg_lo:[0,0,1] neg_hi:[0,0,1]
	v_pk_fma_f32 v[38:39], v[148:149], v[154:155], v[38:39] op_sel_hi:[1,0,1] neg_lo:[0,0,1] neg_hi:[0,0,1]
	v_cndmask_b32_e64 v42, v42, v34, s[74:75]
	v_pk_fma_f32 v[28:29], v[28:29], v[142:143], v[36:37]
	v_pk_fma_f32 v[30:31], v[30:31], v[144:145], v[38:39]
	v_cndmask_b32_e64 v43, v43, v35, s[74:75]
	ds_read_b32 v130, v95 offset:6720
	s_waitcnt lgkmcnt(4)
	v_pk_mul_f32 v[24:25], v[30:31], v[112:113]
	v_pk_mul_f32 v[26:27], v[30:31], v[128:129]
	v_pk_fma_f32 v[24:25], v[28:29], v[110:111], v[24:25]
	v_pk_fma_f32 v[26:27], v[28:29], v[126:127], v[26:27]
	ds_read_b128 v[134:137], v94 offset:6800
	v_add_f32_e32 v34, v24, v25
	v_add_f32_e32 v35, v26, v27
	ds_read_b128 v[150:153], v94 offset:7824
	v_add_f32_dpp v34, v34, v34 quad_perm:[1,0,3,2] row_mask:0xf bank_mask:0xf bound_ctrl:1
	v_add_f32_dpp v35, v35, v35 quad_perm:[1,0,3,2] row_mask:0xf bank_mask:0xf bound_ctrl:1
	ds_read_b128 v[138:141], v94 offset:7056
	v_add_f32_dpp v34, v34, v34 quad_perm:[2,3,0,1] row_mask:0xf bank_mask:0xf bound_ctrl:1
	v_add_f32_dpp v35, v35, v35 quad_perm:[2,3,0,1] row_mask:0xf bank_mask:0xf bound_ctrl:1
	ds_read_b128 v[142:145], v94 offset:7312
	v_add_f32_dpp v34, v34, v34 row_ror:4 row_mask:0xf bank_mask:0xf bound_ctrl:1
	v_add_f32_dpp v35, v35, v35 row_ror:4 row_mask:0xf bank_mask:0xf bound_ctrl:1
	ds_read_b128 v[146:149], v94 offset:7568
	v_add_f32_dpp v34, v34, v34 row_ror:8 row_mask:0xf bank_mask:0xf bound_ctrl:1
	v_add_f32_dpp v35, v35, v35 row_ror:8 row_mask:0xf bank_mask:0xf bound_ctrl:1
	s_waitcnt lgkmcnt(5)
	v_pk_mul_f32 v[36:37], v[114:115], v[34:35] op_sel_hi:[1,0]
	v_pk_mul_f32 v[38:39], v[116:117], v[34:35] op_sel_hi:[1,0]
	v_pk_fma_f32 v[36:37], v[122:123], v[130:131], v[36:37] op_sel_hi:[1,0,1] neg_lo:[0,0,1] neg_hi:[0,0,1]
	v_pk_fma_f32 v[38:39], v[124:125], v[130:131], v[38:39] op_sel_hi:[1,0,1] neg_lo:[0,0,1] neg_hi:[0,0,1]
	v_cndmask_b32_e64 v42, v42, v34, s[82:83]
	v_pk_fma_f32 v[28:29], v[28:29], v[118:119], v[36:37]
	v_pk_fma_f32 v[30:31], v[30:31], v[120:121], v[38:39]
	v_cndmask_b32_e64 v43, v43, v35, s[82:83]
	ds_read_b32 v154, v95 offset:8080
	s_waitcnt lgkmcnt(4)
	v_pk_mul_f32 v[24:25], v[30:31], v[136:137]
	v_pk_mul_f32 v[26:27], v[30:31], v[152:153]
	v_pk_fma_f32 v[24:25], v[28:29], v[134:135], v[24:25]
	v_pk_fma_f32 v[26:27], v[28:29], v[150:151], v[26:27]
	ds_read_b128 v[110:113], v94 offset:8160
	v_add_f32_e32 v34, v24, v25
	v_add_f32_e32 v35, v26, v27
	ds_read_b128 v[126:129], v94 offset:9184
	v_add_f32_dpp v34, v34, v34 quad_perm:[1,0,3,2] row_mask:0xf bank_mask:0xf bound_ctrl:1
	v_add_f32_dpp v35, v35, v35 quad_perm:[1,0,3,2] row_mask:0xf bank_mask:0xf bound_ctrl:1
	ds_read_b128 v[114:117], v94 offset:8416
	v_add_f32_dpp v34, v34, v34 quad_perm:[2,3,0,1] row_mask:0xf bank_mask:0xf bound_ctrl:1
	v_add_f32_dpp v35, v35, v35 quad_perm:[2,3,0,1] row_mask:0xf bank_mask:0xf bound_ctrl:1
	ds_read_b128 v[118:121], v94 offset:8672
	v_add_f32_dpp v34, v34, v34 row_ror:4 row_mask:0xf bank_mask:0xf bound_ctrl:1
	v_add_f32_dpp v35, v35, v35 row_ror:4 row_mask:0xf bank_mask:0xf bound_ctrl:1
	ds_read_b128 v[122:125], v94 offset:8928
	v_add_f32_dpp v34, v34, v34 row_ror:8 row_mask:0xf bank_mask:0xf bound_ctrl:1
	v_add_f32_dpp v35, v35, v35 row_ror:8 row_mask:0xf bank_mask:0xf bound_ctrl:1
	s_waitcnt lgkmcnt(5)
	v_pk_mul_f32 v[36:37], v[138:139], v[34:35] op_sel_hi:[1,0]
	v_pk_mul_f32 v[38:39], v[140:141], v[34:35] op_sel_hi:[1,0]
	v_pk_fma_f32 v[36:37], v[146:147], v[154:155], v[36:37] op_sel_hi:[1,0,1] neg_lo:[0,0,1] neg_hi:[0,0,1]
	v_pk_fma_f32 v[38:39], v[148:149], v[154:155], v[38:39] op_sel_hi:[1,0,1] neg_lo:[0,0,1] neg_hi:[0,0,1]
	v_cndmask_b32_e64 v42, v42, v34, s[48:49]
	v_pk_fma_f32 v[28:29], v[28:29], v[142:143], v[36:37]
	v_pk_fma_f32 v[30:31], v[30:31], v[144:145], v[38:39]
	v_cndmask_b32_e64 v43, v43, v35, s[48:49]
	ds_read_b32 v130, v95 offset:9440
	s_waitcnt lgkmcnt(4)
	v_pk_mul_f32 v[24:25], v[30:31], v[112:113]
	v_pk_mul_f32 v[26:27], v[30:31], v[128:129]
	v_pk_fma_f32 v[24:25], v[28:29], v[110:111], v[24:25]
	v_pk_fma_f32 v[26:27], v[28:29], v[126:127], v[26:27]
	ds_read_b128 v[134:137], v94 offset:9520
	v_add_f32_e32 v34, v24, v25
	v_add_f32_e32 v35, v26, v27
	ds_read_b128 v[150:153], v94 offset:10544
	v_add_f32_dpp v34, v34, v34 quad_perm:[1,0,3,2] row_mask:0xf bank_mask:0xf bound_ctrl:1
	v_add_f32_dpp v35, v35, v35 quad_perm:[1,0,3,2] row_mask:0xf bank_mask:0xf bound_ctrl:1
	ds_read_b128 v[138:141], v94 offset:9776
	v_add_f32_dpp v34, v34, v34 quad_perm:[2,3,0,1] row_mask:0xf bank_mask:0xf bound_ctrl:1
	v_add_f32_dpp v35, v35, v35 quad_perm:[2,3,0,1] row_mask:0xf bank_mask:0xf bound_ctrl:1
	ds_read_b128 v[142:145], v94 offset:10032
	v_add_f32_dpp v34, v34, v34 row_ror:4 row_mask:0xf bank_mask:0xf bound_ctrl:1
	v_add_f32_dpp v35, v35, v35 row_ror:4 row_mask:0xf bank_mask:0xf bound_ctrl:1
	ds_read_b128 v[146:149], v94 offset:10288
	v_add_f32_dpp v34, v34, v34 row_ror:8 row_mask:0xf bank_mask:0xf bound_ctrl:1
	v_add_f32_dpp v35, v35, v35 row_ror:8 row_mask:0xf bank_mask:0xf bound_ctrl:1
	s_waitcnt lgkmcnt(5)
	v_pk_mul_f32 v[36:37], v[114:115], v[34:35] op_sel_hi:[1,0]
	v_pk_mul_f32 v[38:39], v[116:117], v[34:35] op_sel_hi:[1,0]
	v_pk_fma_f32 v[36:37], v[122:123], v[130:131], v[36:37] op_sel_hi:[1,0,1] neg_lo:[0,0,1] neg_hi:[0,0,1]
	v_pk_fma_f32 v[38:39], v[124:125], v[130:131], v[38:39] op_sel_hi:[1,0,1] neg_lo:[0,0,1] neg_hi:[0,0,1]
	v_cndmask_b32_e64 v42, v42, v34, s[38:39]
	v_pk_fma_f32 v[28:29], v[28:29], v[118:119], v[36:37]
	v_pk_fma_f32 v[30:31], v[30:31], v[120:121], v[38:39]
	v_cndmask_b32_e64 v43, v43, v35, s[38:39]
	ds_read_b32 v154, v95 offset:10800
	s_waitcnt lgkmcnt(4)
	v_pk_mul_f32 v[24:25], v[30:31], v[136:137]
	v_pk_mul_f32 v[26:27], v[30:31], v[152:153]
	v_pk_fma_f32 v[24:25], v[28:29], v[134:135], v[24:25]
	v_pk_fma_f32 v[26:27], v[28:29], v[150:151], v[26:27]
	ds_read_b128 v[110:113], v94 offset:10880
	v_add_f32_e32 v34, v24, v25
	v_add_f32_e32 v35, v26, v27
	ds_read_b128 v[126:129], v94 offset:11904
	v_add_f32_dpp v34, v34, v34 quad_perm:[1,0,3,2] row_mask:0xf bank_mask:0xf bound_ctrl:1
	v_add_f32_dpp v35, v35, v35 quad_perm:[1,0,3,2] row_mask:0xf bank_mask:0xf bound_ctrl:1
	ds_read_b128 v[114:117], v94 offset:11136
	v_add_f32_dpp v34, v34, v34 quad_perm:[2,3,0,1] row_mask:0xf bank_mask:0xf bound_ctrl:1
	v_add_f32_dpp v35, v35, v35 quad_perm:[2,3,0,1] row_mask:0xf bank_mask:0xf bound_ctrl:1
	ds_read_b128 v[118:121], v94 offset:11392
	v_add_f32_dpp v34, v34, v34 row_ror:4 row_mask:0xf bank_mask:0xf bound_ctrl:1
	v_add_f32_dpp v35, v35, v35 row_ror:4 row_mask:0xf bank_mask:0xf bound_ctrl:1
	ds_read_b128 v[122:125], v94 offset:11648
	v_add_f32_dpp v34, v34, v34 row_ror:8 row_mask:0xf bank_mask:0xf bound_ctrl:1
	v_add_f32_dpp v35, v35, v35 row_ror:8 row_mask:0xf bank_mask:0xf bound_ctrl:1
	s_waitcnt lgkmcnt(5)
	v_pk_mul_f32 v[36:37], v[138:139], v[34:35] op_sel_hi:[1,0]
	v_pk_mul_f32 v[38:39], v[140:141], v[34:35] op_sel_hi:[1,0]
	v_pk_fma_f32 v[36:37], v[146:147], v[154:155], v[36:37] op_sel_hi:[1,0,1] neg_lo:[0,0,1] neg_hi:[0,0,1]
	v_pk_fma_f32 v[38:39], v[148:149], v[154:155], v[38:39] op_sel_hi:[1,0,1] neg_lo:[0,0,1] neg_hi:[0,0,1]
	v_cndmask_b32_e64 v42, v42, v34, s[42:43]
	v_pk_fma_f32 v[28:29], v[28:29], v[142:143], v[36:37]
	v_pk_fma_f32 v[30:31], v[30:31], v[144:145], v[38:39]
	v_cndmask_b32_e64 v43, v43, v35, s[42:43]
	ds_read_b32 v130, v95 offset:12160
	s_waitcnt lgkmcnt(4)
	v_pk_mul_f32 v[24:25], v[30:31], v[112:113]
	v_pk_mul_f32 v[26:27], v[30:31], v[128:129]
	v_pk_fma_f32 v[24:25], v[28:29], v[110:111], v[24:25]
	v_pk_fma_f32 v[26:27], v[28:29], v[126:127], v[26:27]
	ds_read_b128 v[134:137], v94 offset:12240
	v_add_f32_e32 v34, v24, v25
	v_add_f32_e32 v35, v26, v27
	ds_read_b128 v[150:153], v94 offset:13264
	v_add_f32_dpp v34, v34, v34 quad_perm:[1,0,3,2] row_mask:0xf bank_mask:0xf bound_ctrl:1
	v_add_f32_dpp v35, v35, v35 quad_perm:[1,0,3,2] row_mask:0xf bank_mask:0xf bound_ctrl:1
	ds_read_b128 v[138:141], v94 offset:12496
	v_add_f32_dpp v34, v34, v34 quad_perm:[2,3,0,1] row_mask:0xf bank_mask:0xf bound_ctrl:1
	v_add_f32_dpp v35, v35, v35 quad_perm:[2,3,0,1] row_mask:0xf bank_mask:0xf bound_ctrl:1
	ds_read_b128 v[142:145], v94 offset:12752
	v_add_f32_dpp v34, v34, v34 row_ror:4 row_mask:0xf bank_mask:0xf bound_ctrl:1
	v_add_f32_dpp v35, v35, v35 row_ror:4 row_mask:0xf bank_mask:0xf bound_ctrl:1
	ds_read_b128 v[146:149], v94 offset:13008
	v_add_f32_dpp v34, v34, v34 row_ror:8 row_mask:0xf bank_mask:0xf bound_ctrl:1
	v_add_f32_dpp v35, v35, v35 row_ror:8 row_mask:0xf bank_mask:0xf bound_ctrl:1
	s_waitcnt lgkmcnt(5)
	v_pk_mul_f32 v[36:37], v[114:115], v[34:35] op_sel_hi:[1,0]
	v_pk_mul_f32 v[38:39], v[116:117], v[34:35] op_sel_hi:[1,0]
	v_pk_fma_f32 v[36:37], v[122:123], v[130:131], v[36:37] op_sel_hi:[1,0,1] neg_lo:[0,0,1] neg_hi:[0,0,1]
	v_pk_fma_f32 v[38:39], v[124:125], v[130:131], v[38:39] op_sel_hi:[1,0,1] neg_lo:[0,0,1] neg_hi:[0,0,1]
	v_cndmask_b32_e64 v42, v42, v34, s[44:45]
	v_pk_fma_f32 v[28:29], v[28:29], v[118:119], v[36:37]
	v_pk_fma_f32 v[30:31], v[30:31], v[120:121], v[38:39]
	v_cndmask_b32_e64 v43, v43, v35, s[44:45]
	ds_read_b32 v154, v95 offset:13520
	s_waitcnt lgkmcnt(4)
	v_pk_mul_f32 v[24:25], v[30:31], v[136:137]
	v_pk_mul_f32 v[26:27], v[30:31], v[152:153]
	v_pk_fma_f32 v[24:25], v[28:29], v[134:135], v[24:25]
	v_pk_fma_f32 v[26:27], v[28:29], v[150:151], v[26:27]
	ds_read_b128 v[110:113], v94 offset:13600
	v_add_f32_e32 v34, v24, v25
	v_add_f32_e32 v35, v26, v27
	ds_read_b128 v[126:129], v94 offset:14624
	v_add_f32_dpp v34, v34, v34 quad_perm:[1,0,3,2] row_mask:0xf bank_mask:0xf bound_ctrl:1
	v_add_f32_dpp v35, v35, v35 quad_perm:[1,0,3,2] row_mask:0xf bank_mask:0xf bound_ctrl:1
	ds_read_b128 v[114:117], v94 offset:13856
	v_add_f32_dpp v34, v34, v34 quad_perm:[2,3,0,1] row_mask:0xf bank_mask:0xf bound_ctrl:1
	v_add_f32_dpp v35, v35, v35 quad_perm:[2,3,0,1] row_mask:0xf bank_mask:0xf bound_ctrl:1
	ds_read_b128 v[118:121], v94 offset:14112
	v_add_f32_dpp v34, v34, v34 row_ror:4 row_mask:0xf bank_mask:0xf bound_ctrl:1
	v_add_f32_dpp v35, v35, v35 row_ror:4 row_mask:0xf bank_mask:0xf bound_ctrl:1
	ds_read_b128 v[122:125], v94 offset:14368
	v_add_f32_dpp v34, v34, v34 row_ror:8 row_mask:0xf bank_mask:0xf bound_ctrl:1
	v_add_f32_dpp v35, v35, v35 row_ror:8 row_mask:0xf bank_mask:0xf bound_ctrl:1
	s_waitcnt lgkmcnt(5)
	v_pk_mul_f32 v[36:37], v[138:139], v[34:35] op_sel_hi:[1,0]
	v_pk_mul_f32 v[38:39], v[140:141], v[34:35] op_sel_hi:[1,0]
	v_pk_fma_f32 v[36:37], v[146:147], v[154:155], v[36:37] op_sel_hi:[1,0,1] neg_lo:[0,0,1] neg_hi:[0,0,1]
	v_pk_fma_f32 v[38:39], v[148:149], v[154:155], v[38:39] op_sel_hi:[1,0,1] neg_lo:[0,0,1] neg_hi:[0,0,1]
	v_cndmask_b32_e32 v42, v42, v34, vcc
	v_pk_fma_f32 v[28:29], v[28:29], v[142:143], v[36:37]
	v_pk_fma_f32 v[30:31], v[30:31], v[144:145], v[38:39]
	v_cndmask_b32_e32 v43, v43, v35, vcc
	ds_read_b32 v130, v95 offset:14880
	s_waitcnt lgkmcnt(4)
	v_pk_mul_f32 v[24:25], v[30:31], v[112:113]
	v_pk_mul_f32 v[26:27], v[30:31], v[128:129]
	v_pk_fma_f32 v[24:25], v[28:29], v[110:111], v[24:25]
	v_pk_fma_f32 v[26:27], v[28:29], v[126:127], v[26:27]
	ds_read_b128 v[134:137], v94 offset:14960
	v_add_f32_e32 v34, v24, v25
	v_add_f32_e32 v35, v26, v27
	ds_read_b128 v[150:153], v94 offset:15984
	v_add_f32_dpp v34, v34, v34 quad_perm:[1,0,3,2] row_mask:0xf bank_mask:0xf bound_ctrl:1
	v_add_f32_dpp v35, v35, v35 quad_perm:[1,0,3,2] row_mask:0xf bank_mask:0xf bound_ctrl:1
	ds_read_b128 v[138:141], v94 offset:15216
	v_add_f32_dpp v34, v34, v34 quad_perm:[2,3,0,1] row_mask:0xf bank_mask:0xf bound_ctrl:1
	v_add_f32_dpp v35, v35, v35 quad_perm:[2,3,0,1] row_mask:0xf bank_mask:0xf bound_ctrl:1
	ds_read_b128 v[142:145], v94 offset:15472
	v_add_f32_dpp v34, v34, v34 row_ror:4 row_mask:0xf bank_mask:0xf bound_ctrl:1
	v_add_f32_dpp v35, v35, v35 row_ror:4 row_mask:0xf bank_mask:0xf bound_ctrl:1
	ds_read_b128 v[146:149], v94 offset:15728
	v_add_f32_dpp v34, v34, v34 row_ror:8 row_mask:0xf bank_mask:0xf bound_ctrl:1
	v_add_f32_dpp v35, v35, v35 row_ror:8 row_mask:0xf bank_mask:0xf bound_ctrl:1
	s_waitcnt lgkmcnt(5)
	v_pk_mul_f32 v[36:37], v[114:115], v[34:35] op_sel_hi:[1,0]
	v_pk_mul_f32 v[38:39], v[116:117], v[34:35] op_sel_hi:[1,0]
	v_pk_fma_f32 v[36:37], v[122:123], v[130:131], v[36:37] op_sel_hi:[1,0,1] neg_lo:[0,0,1] neg_hi:[0,0,1]
	v_pk_fma_f32 v[38:39], v[124:125], v[130:131], v[38:39] op_sel_hi:[1,0,1] neg_lo:[0,0,1] neg_hi:[0,0,1]
	v_cndmask_b32_e64 v42, v42, v34, s[58:59]
	v_pk_fma_f32 v[28:29], v[28:29], v[118:119], v[36:37]
	v_pk_fma_f32 v[30:31], v[30:31], v[120:121], v[38:39]
	v_cndmask_b32_e64 v43, v43, v35, s[58:59]
	ds_read_b32 v154, v95 offset:16240
	s_waitcnt lgkmcnt(4)
	v_pk_mul_f32 v[24:25], v[30:31], v[136:137]
	v_pk_mul_f32 v[26:27], v[30:31], v[152:153]
	v_pk_fma_f32 v[24:25], v[28:29], v[134:135], v[24:25]
	v_pk_fma_f32 v[26:27], v[28:29], v[150:151], v[26:27]
	ds_read_b128 v[110:113], v94 offset:16320
	v_add_f32_e32 v34, v24, v25
	v_add_f32_e32 v35, v26, v27
	ds_read_b128 v[126:129], v94 offset:17344
	v_add_f32_dpp v34, v34, v34 quad_perm:[1,0,3,2] row_mask:0xf bank_mask:0xf bound_ctrl:1
	v_add_f32_dpp v35, v35, v35 quad_perm:[1,0,3,2] row_mask:0xf bank_mask:0xf bound_ctrl:1
	ds_read_b128 v[114:117], v94 offset:16576
	v_add_f32_dpp v34, v34, v34 quad_perm:[2,3,0,1] row_mask:0xf bank_mask:0xf bound_ctrl:1
	v_add_f32_dpp v35, v35, v35 quad_perm:[2,3,0,1] row_mask:0xf bank_mask:0xf bound_ctrl:1
	ds_read_b128 v[118:121], v94 offset:16832
	v_add_f32_dpp v34, v34, v34 row_ror:4 row_mask:0xf bank_mask:0xf bound_ctrl:1
	v_add_f32_dpp v35, v35, v35 row_ror:4 row_mask:0xf bank_mask:0xf bound_ctrl:1
	ds_read_b128 v[122:125], v94 offset:17088
	v_add_f32_dpp v34, v34, v34 row_ror:8 row_mask:0xf bank_mask:0xf bound_ctrl:1
	v_add_f32_dpp v35, v35, v35 row_ror:8 row_mask:0xf bank_mask:0xf bound_ctrl:1
	s_waitcnt lgkmcnt(5)
	v_pk_mul_f32 v[36:37], v[138:139], v[34:35] op_sel_hi:[1,0]
	v_pk_mul_f32 v[38:39], v[140:141], v[34:35] op_sel_hi:[1,0]
	v_pk_fma_f32 v[36:37], v[146:147], v[154:155], v[36:37] op_sel_hi:[1,0,1] neg_lo:[0,0,1] neg_hi:[0,0,1]
	v_pk_fma_f32 v[38:39], v[148:149], v[154:155], v[38:39] op_sel_hi:[1,0,1] neg_lo:[0,0,1] neg_hi:[0,0,1]
	v_cndmask_b32_e64 v42, v42, v34, s[60:61]
	v_pk_fma_f32 v[28:29], v[28:29], v[142:143], v[36:37]
	v_pk_fma_f32 v[30:31], v[30:31], v[144:145], v[38:39]
	v_cndmask_b32_e64 v43, v43, v35, s[60:61]
	ds_read_b32 v130, v95 offset:17600
	s_waitcnt lgkmcnt(4)
	v_pk_mul_f32 v[24:25], v[30:31], v[112:113]
	v_pk_mul_f32 v[26:27], v[30:31], v[128:129]
	v_pk_fma_f32 v[24:25], v[28:29], v[110:111], v[24:25]
	v_pk_fma_f32 v[26:27], v[28:29], v[126:127], v[26:27]
	ds_read_b128 v[134:137], v94 offset:17680
	v_add_f32_e32 v34, v24, v25
	v_add_f32_e32 v35, v26, v27
	ds_read_b128 v[150:153], v94 offset:18704
	v_add_f32_dpp v34, v34, v34 quad_perm:[1,0,3,2] row_mask:0xf bank_mask:0xf bound_ctrl:1
	v_add_f32_dpp v35, v35, v35 quad_perm:[1,0,3,2] row_mask:0xf bank_mask:0xf bound_ctrl:1
	ds_read_b128 v[138:141], v94 offset:17936
	v_add_f32_dpp v34, v34, v34 quad_perm:[2,3,0,1] row_mask:0xf bank_mask:0xf bound_ctrl:1
	v_add_f32_dpp v35, v35, v35 quad_perm:[2,3,0,1] row_mask:0xf bank_mask:0xf bound_ctrl:1
	ds_read_b128 v[142:145], v94 offset:18192
	v_add_f32_dpp v34, v34, v34 row_ror:4 row_mask:0xf bank_mask:0xf bound_ctrl:1
	v_add_f32_dpp v35, v35, v35 row_ror:4 row_mask:0xf bank_mask:0xf bound_ctrl:1
	ds_read_b128 v[146:149], v94 offset:18448
	v_add_f32_dpp v34, v34, v34 row_ror:8 row_mask:0xf bank_mask:0xf bound_ctrl:1
	v_add_f32_dpp v35, v35, v35 row_ror:8 row_mask:0xf bank_mask:0xf bound_ctrl:1
	s_waitcnt lgkmcnt(5)
	v_pk_mul_f32 v[36:37], v[114:115], v[34:35] op_sel_hi:[1,0]
	v_pk_mul_f32 v[38:39], v[116:117], v[34:35] op_sel_hi:[1,0]
	v_pk_fma_f32 v[36:37], v[122:123], v[130:131], v[36:37] op_sel_hi:[1,0,1] neg_lo:[0,0,1] neg_hi:[0,0,1]
	v_pk_fma_f32 v[38:39], v[124:125], v[130:131], v[38:39] op_sel_hi:[1,0,1] neg_lo:[0,0,1] neg_hi:[0,0,1]
	v_cndmask_b32_e64 v42, v42, v34, s[62:63]
	v_pk_fma_f32 v[28:29], v[28:29], v[118:119], v[36:37]
	v_pk_fma_f32 v[30:31], v[30:31], v[120:121], v[38:39]
	v_cndmask_b32_e64 v43, v43, v35, s[62:63]
	ds_read_b32 v154, v95 offset:18960
	s_waitcnt lgkmcnt(4)
	v_pk_mul_f32 v[24:25], v[30:31], v[136:137]
	v_pk_mul_f32 v[26:27], v[30:31], v[152:153]
	v_pk_fma_f32 v[24:25], v[28:29], v[134:135], v[24:25]
	v_pk_fma_f32 v[26:27], v[28:29], v[150:151], v[26:27]
	ds_read_b128 v[110:113], v94 offset:19040
	v_add_f32_e32 v34, v24, v25
	v_add_f32_e32 v35, v26, v27
	ds_read_b128 v[126:129], v94 offset:20064
	v_add_f32_dpp v34, v34, v34 quad_perm:[1,0,3,2] row_mask:0xf bank_mask:0xf bound_ctrl:1
	v_add_f32_dpp v35, v35, v35 quad_perm:[1,0,3,2] row_mask:0xf bank_mask:0xf bound_ctrl:1
	ds_read_b128 v[114:117], v94 offset:19296
	v_add_f32_dpp v34, v34, v34 quad_perm:[2,3,0,1] row_mask:0xf bank_mask:0xf bound_ctrl:1
	v_add_f32_dpp v35, v35, v35 quad_perm:[2,3,0,1] row_mask:0xf bank_mask:0xf bound_ctrl:1
	ds_read_b128 v[118:121], v94 offset:19552
	v_add_f32_dpp v34, v34, v34 row_ror:4 row_mask:0xf bank_mask:0xf bound_ctrl:1
	v_add_f32_dpp v35, v35, v35 row_ror:4 row_mask:0xf bank_mask:0xf bound_ctrl:1
	ds_read_b128 v[122:125], v94 offset:19808
	v_add_f32_dpp v34, v34, v34 row_ror:8 row_mask:0xf bank_mask:0xf bound_ctrl:1
	v_add_f32_dpp v35, v35, v35 row_ror:8 row_mask:0xf bank_mask:0xf bound_ctrl:1
	s_waitcnt lgkmcnt(5)
	v_pk_mul_f32 v[36:37], v[138:139], v[34:35] op_sel_hi:[1,0]
	v_pk_mul_f32 v[38:39], v[140:141], v[34:35] op_sel_hi:[1,0]
	v_pk_fma_f32 v[36:37], v[146:147], v[154:155], v[36:37] op_sel_hi:[1,0,1] neg_lo:[0,0,1] neg_hi:[0,0,1]
	v_pk_fma_f32 v[38:39], v[148:149], v[154:155], v[38:39] op_sel_hi:[1,0,1] neg_lo:[0,0,1] neg_hi:[0,0,1]
	v_cndmask_b32_e64 v42, v42, v34, s[66:67]
	v_pk_fma_f32 v[28:29], v[28:29], v[142:143], v[36:37]
	v_pk_fma_f32 v[30:31], v[30:31], v[144:145], v[38:39]
	v_cndmask_b32_e64 v43, v43, v35, s[66:67]
	ds_read_b32 v130, v95 offset:20320
	s_waitcnt lgkmcnt(4)
	v_pk_mul_f32 v[24:25], v[30:31], v[112:113]
	v_pk_mul_f32 v[26:27], v[30:31], v[128:129]
	v_pk_fma_f32 v[24:25], v[28:29], v[110:111], v[24:25]
	v_pk_fma_f32 v[26:27], v[28:29], v[126:127], v[26:27]
	ds_read_b128 v[134:137], v94 offset:20400
	v_add_f32_e32 v34, v24, v25
	v_add_f32_e32 v35, v26, v27
	ds_read_b128 v[150:153], v94 offset:21424
	v_add_f32_dpp v34, v34, v34 quad_perm:[1,0,3,2] row_mask:0xf bank_mask:0xf bound_ctrl:1
	v_add_f32_dpp v35, v35, v35 quad_perm:[1,0,3,2] row_mask:0xf bank_mask:0xf bound_ctrl:1
	ds_read_b128 v[138:141], v94 offset:20656
	v_add_f32_dpp v34, v34, v34 quad_perm:[2,3,0,1] row_mask:0xf bank_mask:0xf bound_ctrl:1
	v_add_f32_dpp v35, v35, v35 quad_perm:[2,3,0,1] row_mask:0xf bank_mask:0xf bound_ctrl:1
	ds_read_b128 v[142:145], v94 offset:20912
	v_add_f32_dpp v34, v34, v34 row_ror:4 row_mask:0xf bank_mask:0xf bound_ctrl:1
	v_add_f32_dpp v35, v35, v35 row_ror:4 row_mask:0xf bank_mask:0xf bound_ctrl:1
	ds_read_b128 v[146:149], v94 offset:21168
	v_add_f32_dpp v34, v34, v34 row_ror:8 row_mask:0xf bank_mask:0xf bound_ctrl:1
	v_add_f32_dpp v35, v35, v35 row_ror:8 row_mask:0xf bank_mask:0xf bound_ctrl:1
	s_waitcnt lgkmcnt(5)
	v_pk_mul_f32 v[36:37], v[114:115], v[34:35] op_sel_hi:[1,0]
	v_pk_mul_f32 v[38:39], v[116:117], v[34:35] op_sel_hi:[1,0]
	v_pk_fma_f32 v[36:37], v[122:123], v[130:131], v[36:37] op_sel_hi:[1,0,1] neg_lo:[0,0,1] neg_hi:[0,0,1]
	v_pk_fma_f32 v[38:39], v[124:125], v[130:131], v[38:39] op_sel_hi:[1,0,1] neg_lo:[0,0,1] neg_hi:[0,0,1]
	v_cndmask_b32_e64 v42, v42, v34, s[64:65]
	v_pk_fma_f32 v[28:29], v[28:29], v[118:119], v[36:37]
	v_pk_fma_f32 v[30:31], v[30:31], v[120:121], v[38:39]
	v_cndmask_b32_e64 v43, v43, v35, s[64:65]
	ds_read_b32 v154, v95 offset:21680
	s_waitcnt lgkmcnt(4)
	v_pk_mul_f32 v[24:25], v[30:31], v[136:137]
	v_pk_mul_f32 v[26:27], v[30:31], v[152:153]
	v_pk_fma_f32 v[24:25], v[28:29], v[134:135], v[24:25]
	v_pk_fma_f32 v[26:27], v[28:29], v[150:151], v[26:27]
	v_add_f32_e32 v34, v24, v25
	v_add_f32_e32 v35, v26, v27
	v_lshl_add_u64 v[70:71], v[70:71], 0, s[2:3]
	v_add_f32_dpp v34, v34, v34 quad_perm:[1,0,3,2] row_mask:0xf bank_mask:0xf bound_ctrl:1
	v_add_f32_dpp v35, v35, v35 quad_perm:[1,0,3,2] row_mask:0xf bank_mask:0xf bound_ctrl:1
	v_lshl_add_u64 v[72:73], v[72:73], 0, s[20:21]
	v_add_f32_dpp v34, v34, v34 quad_perm:[2,3,0,1] row_mask:0xf bank_mask:0xf bound_ctrl:1
	v_add_f32_dpp v35, v35, v35 quad_perm:[2,3,0,1] row_mask:0xf bank_mask:0xf bound_ctrl:1
	v_lshl_add_u64 v[74:75], v[74:75], 0, s[20:21]
	v_add_f32_dpp v34, v34, v34 row_ror:4 row_mask:0xf bank_mask:0xf bound_ctrl:1
	v_add_f32_dpp v35, v35, v35 row_ror:4 row_mask:0xf bank_mask:0xf bound_ctrl:1
	s_nop 0
	v_add_f32_dpp v34, v34, v34 row_ror:8 row_mask:0xf bank_mask:0xf bound_ctrl:1
	v_add_f32_dpp v35, v35, v35 row_ror:8 row_mask:0xf bank_mask:0xf bound_ctrl:1
	s_waitcnt lgkmcnt(0)
	v_pk_mul_f32 v[36:37], v[138:139], v[34:35] op_sel_hi:[1,0]
	v_pk_mul_f32 v[38:39], v[140:141], v[34:35] op_sel_hi:[1,0]
	v_pk_fma_f32 v[36:37], v[146:147], v[154:155], v[36:37] op_sel_hi:[1,0,1] neg_lo:[0,0,1] neg_hi:[0,0,1]
	v_pk_fma_f32 v[38:39], v[148:149], v[154:155], v[38:39] op_sel_hi:[1,0,1] neg_lo:[0,0,1] neg_hi:[0,0,1]
	v_cndmask_b32_e64 v42, v42, v34, s[68:69]
	v_pk_fma_f32 v[28:29], v[28:29], v[142:143], v[36:37]
	v_pk_fma_f32 v[30:31], v[30:31], v[144:145], v[38:39]
	v_cndmask_b32_e64 v43, v43, v35, s[68:69]
	v_lshl_add_u64 v[24:25], v[68:69], 0, s[0:1]
	s_add_u32 s0, s0, 0x1000
	s_addc_u32 s1, s1, 0
	s_add_i32 s24, s24, 1
	v_fma_f32 v40, -v44, v42, v43
	s_cmp_lg_u32 s0, 0xac000
	v_fmac_f32_e32 v40, v48, v45
	global_store_dword v[24:25], v40, off
	s_barrier
	s_cbranch_scc0 .LBB0_81

.LBB0_151:
	s_bitcmp1_b32 s24, 0
	s_cselect_b32 s2, 0x5500, 0
	v_lshl_or_b32 v94, v93, 2, s2
	v_lshl_add_u32 v95, v0, 2, s2
	v_mov_b32_e32 v96, s2
	v_mul_u32_u24_e32 v46, 0x154, v93
	v_add_u32_e32 v47, v46, v96
	v_add_u32_e32 v46, v46, v95
	ds_read_b64 v[44:45], v47 offset:1344
	ds_read_b32 v48, v46 offset:1280
	ds_read_b128 v[110:113], v94
	ds_read_b128 v[126:129], v94 offset:1024
	ds_read_b128 v[114:117], v94 offset:256
	ds_read_b128 v[118:121], v94 offset:512
	ds_read_b128 v[122:125], v94 offset:768
	ds_read_b32 v130, v95 offset:1280
	s_mov_b64 s[2:3], 0x100
	s_mov_b64 s[20:21], 0x800
	s_waitcnt lgkmcnt(4)
	v_pk_mul_f32 v[24:25], v[30:31], v[112:113]
	v_pk_mul_f32 v[26:27], v[30:31], v[128:129]
	v_pk_fma_f32 v[24:25], v[28:29], v[110:111], v[24:25]
	v_pk_fma_f32 v[26:27], v[28:29], v[126:127], v[26:27]
	ds_read_b128 v[134:137], v94 offset:1360
	v_add_f32_e32 v34, v24, v25
	v_add_f32_e32 v35, v26, v27
	ds_read_b128 v[150:153], v94 offset:2384
	v_add_f32_dpp v34, v34, v34 quad_perm:[1,0,3,2] row_mask:0xf bank_mask:0xf bound_ctrl:1
	v_add_f32_dpp v35, v35, v35 quad_perm:[1,0,3,2] row_mask:0xf bank_mask:0xf bound_ctrl:1
	ds_read_b128 v[138:141], v94 offset:1616
	v_add_f32_dpp v34, v34, v34 quad_perm:[2,3,0,1] row_mask:0xf bank_mask:0xf bound_ctrl:1
	v_add_f32_dpp v35, v35, v35 quad_perm:[2,3,0,1] row_mask:0xf bank_mask:0xf bound_ctrl:1
	ds_read_b128 v[142:145], v94 offset:1872
	v_add_f32_dpp v34, v34, v34 row_ror:4 row_mask:0xf bank_mask:0xf bound_ctrl:1
	v_add_f32_dpp v35, v35, v35 row_ror:4 row_mask:0xf bank_mask:0xf bound_ctrl:1
	ds_read_b128 v[146:149], v94 offset:2128
	v_add_f32_dpp v34, v34, v34 row_ror:8 row_mask:0xf bank_mask:0xf bound_ctrl:1
	v_add_f32_dpp v35, v35, v35 row_ror:8 row_mask:0xf bank_mask:0xf bound_ctrl:1
	s_waitcnt lgkmcnt(5)
	v_pk_mul_f32 v[36:37], v[114:115], v[34:35] op_sel_hi:[1,0]
	v_pk_mul_f32 v[38:39], v[116:117], v[34:35] op_sel_hi:[1,0]
	v_pk_fma_f32 v[36:37], v[122:123], v[130:131], v[36:37] op_sel_hi:[1,0,1] neg_lo:[0,0,1] neg_hi:[0,0,1]
	v_pk_fma_f32 v[38:39], v[124:125], v[130:131], v[38:39] op_sel_hi:[1,0,1] neg_lo:[0,0,1] neg_hi:[0,0,1]
	v_cndmask_b32_e64 v42, 0, v34, s[72:73]
	v_pk_fma_f32 v[28:29], v[28:29], v[118:119], v[36:37]
	v_pk_fma_f32 v[30:31], v[30:31], v[120:121], v[38:39]
	v_cndmask_b32_e64 v43, 0, v35, s[72:73]
	ds_read_b32 v154, v95 offset:2640
	s_waitcnt lgkmcnt(4)
	v_pk_mul_f32 v[24:25], v[30:31], v[136:137]
	v_pk_mul_f32 v[26:27], v[30:31], v[152:153]
	v_pk_fma_f32 v[24:25], v[28:29], v[134:135], v[24:25]
	v_pk_fma_f32 v[26:27], v[28:29], v[150:151], v[26:27]
	ds_read_b128 v[110:113], v94 offset:2720
	v_add_f32_e32 v34, v24, v25
	v_add_f32_e32 v35, v26, v27
	ds_read_b128 v[126:129], v94 offset:3744
	v_add_f32_dpp v34, v34, v34 quad_perm:[1,0,3,2] row_mask:0xf bank_mask:0xf bound_ctrl:1
	v_add_f32_dpp v35, v35, v35 quad_perm:[1,0,3,2] row_mask:0xf bank_mask:0xf bound_ctrl:1
	ds_read_b128 v[114:117], v94 offset:2976
	v_add_f32_dpp v34, v34, v34 quad_perm:[2,3,0,1] row_mask:0xf bank_mask:0xf bound_ctrl:1
	v_add_f32_dpp v35, v35, v35 quad_perm:[2,3,0,1] row_mask:0xf bank_mask:0xf bound_ctrl:1
	ds_read_b128 v[118:121], v94 offset:3232
	v_add_f32_dpp v34, v34, v34 row_ror:4 row_mask:0xf bank_mask:0xf bound_ctrl:1
	v_add_f32_dpp v35, v35, v35 row_ror:4 row_mask:0xf bank_mask:0xf bound_ctrl:1
	ds_read_b128 v[122:125], v94 offset:3488
	v_add_f32_dpp v34, v34, v34 row_ror:8 row_mask:0xf bank_mask:0xf bound_ctrl:1
	v_add_f32_dpp v35, v35, v35 row_ror:8 row_mask:0xf bank_mask:0xf bound_ctrl:1
	s_waitcnt lgkmcnt(5)
	v_pk_mul_f32 v[36:37], v[138:139], v[34:35] op_sel_hi:[1,0]
	v_pk_mul_f32 v[38:39], v[140:141], v[34:35] op_sel_hi:[1,0]
	v_pk_fma_f32 v[36:37], v[146:147], v[154:155], v[36:37] op_sel_hi:[1,0,1] neg_lo:[0,0,1] neg_hi:[0,0,1]
	v_pk_fma_f32 v[38:39], v[148:149], v[154:155], v[38:39] op_sel_hi:[1,0,1] neg_lo:[0,0,1] neg_hi:[0,0,1]
	v_cndmask_b32_e64 v42, v42, v34, s[30:31]
	v_pk_fma_f32 v[28:29], v[28:29], v[142:143], v[36:37]
	v_pk_fma_f32 v[30:31], v[30:31], v[144:145], v[38:39]
	v_cndmask_b32_e64 v43, v43, v35, s[30:31]
	ds_read_b32 v130, v95 offset:4000
	s_waitcnt lgkmcnt(4)
	v_pk_mul_f32 v[24:25], v[30:31], v[112:113]
	v_pk_mul_f32 v[26:27], v[30:31], v[128:129]
	v_pk_fma_f32 v[24:25], v[28:29], v[110:111], v[24:25]
	v_pk_fma_f32 v[26:27], v[28:29], v[126:127], v[26:27]
	ds_read_b128 v[134:137], v94 offset:4080
	v_add_f32_e32 v34, v24, v25
	v_add_f32_e32 v35, v26, v27
	ds_read_b128 v[150:153], v94 offset:5104
	v_add_f32_dpp v34, v34, v34 quad_perm:[1,0,3,2] row_mask:0xf bank_mask:0xf bound_ctrl:1
	v_add_f32_dpp v35, v35, v35 quad_perm:[1,0,3,2] row_mask:0xf bank_mask:0xf bound_ctrl:1
	ds_read_b128 v[138:141], v94 offset:4336
	v_add_f32_dpp v34, v34, v34 quad_perm:[2,3,0,1] row_mask:0xf bank_mask:0xf bound_ctrl:1
	v_add_f32_dpp v35, v35, v35 quad_perm:[2,3,0,1] row_mask:0xf bank_mask:0xf bound_ctrl:1
	ds_read_b128 v[142:145], v94 offset:4592
	v_add_f32_dpp v34, v34, v34 row_ror:4 row_mask:0xf bank_mask:0xf bound_ctrl:1
	v_add_f32_dpp v35, v35, v35 row_ror:4 row_mask:0xf bank_mask:0xf bound_ctrl:1
	ds_read_b128 v[146:149], v94 offset:4848
	v_add_f32_dpp v34, v34, v34 row_ror:8 row_mask:0xf bank_mask:0xf bound_ctrl:1
	v_add_f32_dpp v35, v35, v35 row_ror:8 row_mask:0xf bank_mask:0xf bound_ctrl:1
	s_waitcnt lgkmcnt(5)
	v_pk_mul_f32 v[36:37], v[114:115], v[34:35] op_sel_hi:[1,0]
	v_pk_mul_f32 v[38:39], v[116:117], v[34:35] op_sel_hi:[1,0]
	v_pk_fma_f32 v[36:37], v[122:123], v[130:131], v[36:37] op_sel_hi:[1,0,1] neg_lo:[0,0,1] neg_hi:[0,0,1]
	v_pk_fma_f32 v[38:39], v[124:125], v[130:131], v[38:39] op_sel_hi:[1,0,1] neg_lo:[0,0,1] neg_hi:[0,0,1]
	v_cndmask_b32_e64 v42, v42, v34, s[70:71]
	v_pk_fma_f32 v[28:29], v[28:29], v[118:119], v[36:37]
	v_pk_fma_f32 v[30:31], v[30:31], v[120:121], v[38:39]
	v_cndmask_b32_e64 v43, v43, v35, s[70:71]
	ds_read_b32 v154, v95 offset:5360
	s_waitcnt lgkmcnt(4)
	v_pk_mul_f32 v[24:25], v[30:31], v[136:137]
	v_pk_mul_f32 v[26:27], v[30:31], v[152:153]
	v_pk_fma_f32 v[24:25], v[28:29], v[134:135], v[24:25]
	v_pk_fma_f32 v[26:27], v[28:29], v[150:151], v[26:27]
	ds_read_b128 v[110:113], v94 offset:5440
	v_add_f32_e32 v34, v24, v25
	v_add_f32_e32 v35, v26, v27
	ds_read_b128 v[126:129], v94 offset:6464
	v_add_f32_dpp v34, v34, v34 quad_perm:[1,0,3,2] row_mask:0xf bank_mask:0xf bound_ctrl:1
	v_add_f32_dpp v35, v35, v35 quad_perm:[1,0,3,2] row_mask:0xf bank_mask:0xf bound_ctrl:1
	ds_read_b128 v[114:117], v94 offset:5696
	v_add_f32_dpp v34, v34, v34 quad_perm:[2,3,0,1] row_mask:0xf bank_mask:0xf bound_ctrl:1
	v_add_f32_dpp v35, v35, v35 quad_perm:[2,3,0,1] row_mask:0xf bank_mask:0xf bound_ctrl:1
	ds_read_b128 v[118:121], v94 offset:5952
	v_add_f32_dpp v34, v34, v34 row_ror:4 row_mask:0xf bank_mask:0xf bound_ctrl:1
	v_add_f32_dpp v35, v35, v35 row_ror:4 row_mask:0xf bank_mask:0xf bound_ctrl:1
	ds_read_b128 v[122:125], v94 offset:6208
	v_add_f32_dpp v34, v34, v34 row_ror:8 row_mask:0xf bank_mask:0xf bound_ctrl:1
	v_add_f32_dpp v35, v35, v35 row_ror:8 row_mask:0xf bank_mask:0xf bound_ctrl:1
	s_waitcnt lgkmcnt(5)
	v_pk_mul_f32 v[36:37], v[138:139], v[34:35] op_sel_hi:[1,0]
	v_pk_mul_f32 v[38:39], v[140:141], v[34:35] op_sel_hi:[1,0]
	v_pk_fma_f32 v[36:37], v[146:147], v[154:155], v[36:37] op_sel_hi:[1,0,1] neg_lo:[0,0,1] neg_hi:[0,0,1]
	v_pk_fma_f32 v[38:39], v[148:149], v[154:155], v[38:39] op_sel_hi:[1,0,1] neg_lo:[0,0,1] neg_hi:[0,0,1]
	v_cndmask_b32_e64 v42, v42, v34, s[40:41]
	v_pk_fma_f32 v[28:29], v[28:29], v[142:143], v[36:37]
	v_pk_fma_f32 v[30:31], v[30:31], v[144:145], v[38:39]
	v_cndmask_b32_e64 v43, v43, v35, s[40:41]
	ds_read_b32 v130, v95 offset:6720
	s_waitcnt lgkmcnt(4)
	v_pk_mul_f32 v[24:25], v[30:31], v[112:113]
	v_pk_mul_f32 v[26:27], v[30:31], v[128:129]
	v_pk_fma_f32 v[24:25], v[28:29], v[110:111], v[24:25]
	v_pk_fma_f32 v[26:27], v[28:29], v[126:127], v[26:27]
	ds_read_b128 v[134:137], v94 offset:6800
	v_add_f32_e32 v34, v24, v25
	v_add_f32_e32 v35, v26, v27
	ds_read_b128 v[150:153], v94 offset:7824
	v_add_f32_dpp v34, v34, v34 quad_perm:[1,0,3,2] row_mask:0xf bank_mask:0xf bound_ctrl:1
	v_add_f32_dpp v35, v35, v35 quad_perm:[1,0,3,2] row_mask:0xf bank_mask:0xf bound_ctrl:1
	ds_read_b128 v[138:141], v94 offset:7056
	v_add_f32_dpp v34, v34, v34 quad_perm:[2,3,0,1] row_mask:0xf bank_mask:0xf bound_ctrl:1
	v_add_f32_dpp v35, v35, v35 quad_perm:[2,3,0,1] row_mask:0xf bank_mask:0xf bound_ctrl:1
	ds_read_b128 v[142:145], v94 offset:7312
	v_add_f32_dpp v34, v34, v34 row_ror:4 row_mask:0xf bank_mask:0xf bound_ctrl:1
	v_add_f32_dpp v35, v35, v35 row_ror:4 row_mask:0xf bank_mask:0xf bound_ctrl:1
	ds_read_b128 v[146:149], v94 offset:7568
	v_add_f32_dpp v34, v34, v34 row_ror:8 row_mask:0xf bank_mask:0xf bound_ctrl:1
	v_add_f32_dpp v35, v35, v35 row_ror:8 row_mask:0xf bank_mask:0xf bound_ctrl:1
	s_waitcnt lgkmcnt(5)
	v_pk_mul_f32 v[36:37], v[114:115], v[34:35] op_sel_hi:[1,0]
	v_pk_mul_f32 v[38:39], v[116:117], v[34:35] op_sel_hi:[1,0]
	v_pk_fma_f32 v[36:37], v[122:123], v[130:131], v[36:37] op_sel_hi:[1,0,1] neg_lo:[0,0,1] neg_hi:[0,0,1]
	v_pk_fma_f32 v[38:39], v[124:125], v[130:131], v[38:39] op_sel_hi:[1,0,1] neg_lo:[0,0,1] neg_hi:[0,0,1]
	v_cndmask_b32_e64 v42, v42, v34, s[42:43]
	v_pk_fma_f32 v[28:29], v[28:29], v[118:119], v[36:37]
	v_pk_fma_f32 v[30:31], v[30:31], v[120:121], v[38:39]
	v_cndmask_b32_e64 v43, v43, v35, s[42:43]
	ds_read_b32 v154, v95 offset:8080
	s_waitcnt lgkmcnt(4)
	v_pk_mul_f32 v[24:25], v[30:31], v[136:137]
	v_pk_mul_f32 v[26:27], v[30:31], v[152:153]
	v_pk_fma_f32 v[24:25], v[28:29], v[134:135], v[24:25]
	v_pk_fma_f32 v[26:27], v[28:29], v[150:151], v[26:27]
	ds_read_b128 v[110:113], v94 offset:8160
	v_add_f32_e32 v34, v24, v25
	v_add_f32_e32 v35, v26, v27
	ds_read_b128 v[126:129], v94 offset:9184
	v_add_f32_dpp v34, v34, v34 quad_perm:[1,0,3,2] row_mask:0xf bank_mask:0xf bound_ctrl:1
	v_add_f32_dpp v35, v35, v35 quad_perm:[1,0,3,2] row_mask:0xf bank_mask:0xf bound_ctrl:1
	ds_read_b128 v[114:117], v94 offset:8416
	v_add_f32_dpp v34, v34, v34 quad_perm:[2,3,0,1] row_mask:0xf bank_mask:0xf bound_ctrl:1
	v_add_f32_dpp v35, v35, v35 quad_perm:[2,3,0,1] row_mask:0xf bank_mask:0xf bound_ctrl:1
	ds_read_b128 v[118:121], v94 offset:8672
	v_add_f32_dpp v34, v34, v34 row_ror:4 row_mask:0xf bank_mask:0xf bound_ctrl:1
	v_add_f32_dpp v35, v35, v35 row_ror:4 row_mask:0xf bank_mask:0xf bound_ctrl:1
	ds_read_b128 v[122:125], v94 offset:8928
	v_add_f32_dpp v34, v34, v34 row_ror:8 row_mask:0xf bank_mask:0xf bound_ctrl:1
	v_add_f32_dpp v35, v35, v35 row_ror:8 row_mask:0xf bank_mask:0xf bound_ctrl:1
	s_waitcnt lgkmcnt(5)
	v_pk_mul_f32 v[36:37], v[138:139], v[34:35] op_sel_hi:[1,0]
	v_pk_mul_f32 v[38:39], v[140:141], v[34:35] op_sel_hi:[1,0]
	v_pk_fma_f32 v[36:37], v[146:147], v[154:155], v[36:37] op_sel_hi:[1,0,1] neg_lo:[0,0,1] neg_hi:[0,0,1]
	v_pk_fma_f32 v[38:39], v[148:149], v[154:155], v[38:39] op_sel_hi:[1,0,1] neg_lo:[0,0,1] neg_hi:[0,0,1]
	v_cndmask_b32_e64 v42, v42, v34, s[44:45]
	v_pk_fma_f32 v[28:29], v[28:29], v[142:143], v[36:37]
	v_pk_fma_f32 v[30:31], v[30:31], v[144:145], v[38:39]
	v_cndmask_b32_e64 v43, v43, v35, s[44:45]
	ds_read_b32 v130, v95 offset:9440
	s_waitcnt lgkmcnt(4)
	v_pk_mul_f32 v[24:25], v[30:31], v[112:113]
	v_pk_mul_f32 v[26:27], v[30:31], v[128:129]
	v_pk_fma_f32 v[24:25], v[28:29], v[110:111], v[24:25]
	v_pk_fma_f32 v[26:27], v[28:29], v[126:127], v[26:27]
	ds_read_b128 v[134:137], v94 offset:9520
	v_add_f32_e32 v34, v24, v25
	v_add_f32_e32 v35, v26, v27
	ds_read_b128 v[150:153], v94 offset:10544
	v_add_f32_dpp v34, v34, v34 quad_perm:[1,0,3,2] row_mask:0xf bank_mask:0xf bound_ctrl:1
	v_add_f32_dpp v35, v35, v35 quad_perm:[1,0,3,2] row_mask:0xf bank_mask:0xf bound_ctrl:1
	ds_read_b128 v[138:141], v94 offset:9776
	v_add_f32_dpp v34, v34, v34 quad_perm:[2,3,0,1] row_mask:0xf bank_mask:0xf bound_ctrl:1
	v_add_f32_dpp v35, v35, v35 quad_perm:[2,3,0,1] row_mask:0xf bank_mask:0xf bound_ctrl:1
	ds_read_b128 v[142:145], v94 offset:10032
	v_add_f32_dpp v34, v34, v34 row_ror:4 row_mask:0xf bank_mask:0xf bound_ctrl:1
	v_add_f32_dpp v35, v35, v35 row_ror:4 row_mask:0xf bank_mask:0xf bound_ctrl:1
	ds_read_b128 v[146:149], v94 offset:10288
	v_add_f32_dpp v34, v34, v34 row_ror:8 row_mask:0xf bank_mask:0xf bound_ctrl:1
	v_add_f32_dpp v35, v35, v35 row_ror:8 row_mask:0xf bank_mask:0xf bound_ctrl:1
	s_waitcnt lgkmcnt(5)
	v_pk_mul_f32 v[36:37], v[114:115], v[34:35] op_sel_hi:[1,0]
	v_pk_mul_f32 v[38:39], v[116:117], v[34:35] op_sel_hi:[1,0]
	v_pk_fma_f32 v[36:37], v[122:123], v[130:131], v[36:37] op_sel_hi:[1,0,1] neg_lo:[0,0,1] neg_hi:[0,0,1]
	v_pk_fma_f32 v[38:39], v[124:125], v[130:131], v[38:39] op_sel_hi:[1,0,1] neg_lo:[0,0,1] neg_hi:[0,0,1]
	v_cndmask_b32_e64 v42, v42, v34, s[46:47]
	v_pk_fma_f32 v[28:29], v[28:29], v[118:119], v[36:37]
	v_pk_fma_f32 v[30:31], v[30:31], v[120:121], v[38:39]
	v_cndmask_b32_e64 v43, v43, v35, s[46:47]
	ds_read_b32 v154, v95 offset:10800
	s_waitcnt lgkmcnt(4)
	v_pk_mul_f32 v[24:25], v[30:31], v[136:137]
	v_pk_mul_f32 v[26:27], v[30:31], v[152:153]
	v_pk_fma_f32 v[24:25], v[28:29], v[134:135], v[24:25]
	v_pk_fma_f32 v[26:27], v[28:29], v[150:151], v[26:27]
	ds_read_b128 v[110:113], v94 offset:10880
	v_add_f32_e32 v34, v24, v25
	v_add_f32_e32 v35, v26, v27
	ds_read_b128 v[126:129], v94 offset:11904
	v_add_f32_dpp v34, v34, v34 quad_perm:[1,0,3,2] row_mask:0xf bank_mask:0xf bound_ctrl:1
	v_add_f32_dpp v35, v35, v35 quad_perm:[1,0,3,2] row_mask:0xf bank_mask:0xf bound_ctrl:1
	ds_read_b128 v[114:117], v94 offset:11136
	v_add_f32_dpp v34, v34, v34 quad_perm:[2,3,0,1] row_mask:0xf bank_mask:0xf bound_ctrl:1
	v_add_f32_dpp v35, v35, v35 quad_perm:[2,3,0,1] row_mask:0xf bank_mask:0xf bound_ctrl:1
	ds_read_b128 v[118:121], v94 offset:11392
	v_add_f32_dpp v34, v34, v34 row_ror:4 row_mask:0xf bank_mask:0xf bound_ctrl:1
	v_add_f32_dpp v35, v35, v35 row_ror:4 row_mask:0xf bank_mask:0xf bound_ctrl:1
	ds_read_b128 v[122:125], v94 offset:11648
	v_add_f32_dpp v34, v34, v34 row_ror:8 row_mask:0xf bank_mask:0xf bound_ctrl:1
	v_add_f32_dpp v35, v35, v35 row_ror:8 row_mask:0xf bank_mask:0xf bound_ctrl:1
	s_waitcnt lgkmcnt(5)
	v_pk_mul_f32 v[36:37], v[138:139], v[34:35] op_sel_hi:[1,0]
	v_pk_mul_f32 v[38:39], v[140:141], v[34:35] op_sel_hi:[1,0]
	v_pk_fma_f32 v[36:37], v[146:147], v[154:155], v[36:37] op_sel_hi:[1,0,1] neg_lo:[0,0,1] neg_hi:[0,0,1]
	v_pk_fma_f32 v[38:39], v[148:149], v[154:155], v[38:39] op_sel_hi:[1,0,1] neg_lo:[0,0,1] neg_hi:[0,0,1]
	v_cndmask_b32_e64 v42, v42, v34, s[58:59]
	v_pk_fma_f32 v[28:29], v[28:29], v[142:143], v[36:37]
	v_pk_fma_f32 v[30:31], v[30:31], v[144:145], v[38:39]
	v_cndmask_b32_e64 v43, v43, v35, s[58:59]
	ds_read_b32 v130, v95 offset:12160
	s_waitcnt lgkmcnt(4)
	v_pk_mul_f32 v[24:25], v[30:31], v[112:113]
	v_pk_mul_f32 v[26:27], v[30:31], v[128:129]
	v_pk_fma_f32 v[24:25], v[28:29], v[110:111], v[24:25]
	v_pk_fma_f32 v[26:27], v[28:29], v[126:127], v[26:27]
	ds_read_b128 v[134:137], v94 offset:12240
	v_add_f32_e32 v34, v24, v25
	v_add_f32_e32 v35, v26, v27
	ds_read_b128 v[150:153], v94 offset:13264
	v_add_f32_dpp v34, v34, v34 quad_perm:[1,0,3,2] row_mask:0xf bank_mask:0xf bound_ctrl:1
	v_add_f32_dpp v35, v35, v35 quad_perm:[1,0,3,2] row_mask:0xf bank_mask:0xf bound_ctrl:1
	ds_read_b128 v[138:141], v94 offset:12496
	v_add_f32_dpp v34, v34, v34 quad_perm:[2,3,0,1] row_mask:0xf bank_mask:0xf bound_ctrl:1
	v_add_f32_dpp v35, v35, v35 quad_perm:[2,3,0,1] row_mask:0xf bank_mask:0xf bound_ctrl:1
	ds_read_b128 v[142:145], v94 offset:12752
	v_add_f32_dpp v34, v34, v34 row_ror:4 row_mask:0xf bank_mask:0xf bound_ctrl:1
	v_add_f32_dpp v35, v35, v35 row_ror:4 row_mask:0xf bank_mask:0xf bound_ctrl:1
	ds_read_b128 v[146:149], v94 offset:13008
	v_add_f32_dpp v34, v34, v34 row_ror:8 row_mask:0xf bank_mask:0xf bound_ctrl:1
	v_add_f32_dpp v35, v35, v35 row_ror:8 row_mask:0xf bank_mask:0xf bound_ctrl:1
	s_waitcnt lgkmcnt(5)
	v_pk_mul_f32 v[36:37], v[114:115], v[34:35] op_sel_hi:[1,0]
	v_pk_mul_f32 v[38:39], v[116:117], v[34:35] op_sel_hi:[1,0]
	v_pk_fma_f32 v[36:37], v[122:123], v[130:131], v[36:37] op_sel_hi:[1,0,1] neg_lo:[0,0,1] neg_hi:[0,0,1]
	v_pk_fma_f32 v[38:39], v[124:125], v[130:131], v[38:39] op_sel_hi:[1,0,1] neg_lo:[0,0,1] neg_hi:[0,0,1]
	v_cndmask_b32_e64 v42, v42, v34, s[60:61]
	v_pk_fma_f32 v[28:29], v[28:29], v[118:119], v[36:37]
	v_pk_fma_f32 v[30:31], v[30:31], v[120:121], v[38:39]
	v_cndmask_b32_e64 v43, v43, v35, s[60:61]
	ds_read_b32 v154, v95 offset:13520
	s_waitcnt lgkmcnt(4)
	v_pk_mul_f32 v[24:25], v[30:31], v[136:137]
	v_pk_mul_f32 v[26:27], v[30:31], v[152:153]
	v_pk_fma_f32 v[24:25], v[28:29], v[134:135], v[24:25]
	v_pk_fma_f32 v[26:27], v[28:29], v[150:151], v[26:27]
	ds_read_b128 v[110:113], v94 offset:13600
	v_add_f32_e32 v34, v24, v25
	v_add_f32_e32 v35, v26, v27
	ds_read_b128 v[126:129], v94 offset:14624
	v_add_f32_dpp v34, v34, v34 quad_perm:[1,0,3,2] row_mask:0xf bank_mask:0xf bound_ctrl:1
	v_add_f32_dpp v35, v35, v35 quad_perm:[1,0,3,2] row_mask:0xf bank_mask:0xf bound_ctrl:1
	ds_read_b128 v[114:117], v94 offset:13856
	v_add_f32_dpp v34, v34, v34 quad_perm:[2,3,0,1] row_mask:0xf bank_mask:0xf bound_ctrl:1
	v_add_f32_dpp v35, v35, v35 quad_perm:[2,3,0,1] row_mask:0xf bank_mask:0xf bound_ctrl:1
	ds_read_b128 v[118:121], v94 offset:14112
	v_add_f32_dpp v34, v34, v34 row_ror:4 row_mask:0xf bank_mask:0xf bound_ctrl:1
	v_add_f32_dpp v35, v35, v35 row_ror:4 row_mask:0xf bank_mask:0xf bound_ctrl:1
	ds_read_b128 v[122:125], v94 offset:14368
	v_add_f32_dpp v34, v34, v34 row_ror:8 row_mask:0xf bank_mask:0xf bound_ctrl:1
	v_add_f32_dpp v35, v35, v35 row_ror:8 row_mask:0xf bank_mask:0xf bound_ctrl:1
	s_waitcnt lgkmcnt(5)
	v_pk_mul_f32 v[36:37], v[138:139], v[34:35] op_sel_hi:[1,0]
	v_pk_mul_f32 v[38:39], v[140:141], v[34:35] op_sel_hi:[1,0]
	v_pk_fma_f32 v[36:37], v[146:147], v[154:155], v[36:37] op_sel_hi:[1,0,1] neg_lo:[0,0,1] neg_hi:[0,0,1]
	v_pk_fma_f32 v[38:39], v[148:149], v[154:155], v[38:39] op_sel_hi:[1,0,1] neg_lo:[0,0,1] neg_hi:[0,0,1]
	v_cndmask_b32_e64 v42, v42, v34, s[62:63]
	v_pk_fma_f32 v[28:29], v[28:29], v[142:143], v[36:37]
	v_pk_fma_f32 v[30:31], v[30:31], v[144:145], v[38:39]
	v_cndmask_b32_e64 v43, v43, v35, s[62:63]
	ds_read_b32 v130, v95 offset:14880
	s_waitcnt lgkmcnt(4)
	v_pk_mul_f32 v[24:25], v[30:31], v[112:113]
	v_pk_mul_f32 v[26:27], v[30:31], v[128:129]
	v_pk_fma_f32 v[24:25], v[28:29], v[110:111], v[24:25]
	v_pk_fma_f32 v[26:27], v[28:29], v[126:127], v[26:27]
	ds_read_b128 v[134:137], v94 offset:14960
	v_add_f32_e32 v34, v24, v25
	v_add_f32_e32 v35, v26, v27
	ds_read_b128 v[150:153], v94 offset:15984
	v_add_f32_dpp v34, v34, v34 quad_perm:[1,0,3,2] row_mask:0xf bank_mask:0xf bound_ctrl:1
	v_add_f32_dpp v35, v35, v35 quad_perm:[1,0,3,2] row_mask:0xf bank_mask:0xf bound_ctrl:1
	ds_read_b128 v[138:141], v94 offset:15216
	v_add_f32_dpp v34, v34, v34 quad_perm:[2,3,0,1] row_mask:0xf bank_mask:0xf bound_ctrl:1
	v_add_f32_dpp v35, v35, v35 quad_perm:[2,3,0,1] row_mask:0xf bank_mask:0xf bound_ctrl:1
	ds_read_b128 v[142:145], v94 offset:15472
	v_add_f32_dpp v34, v34, v34 row_ror:4 row_mask:0xf bank_mask:0xf bound_ctrl:1
	v_add_f32_dpp v35, v35, v35 row_ror:4 row_mask:0xf bank_mask:0xf bound_ctrl:1
	ds_read_b128 v[146:149], v94 offset:15728
	v_add_f32_dpp v34, v34, v34 row_ror:8 row_mask:0xf bank_mask:0xf bound_ctrl:1
	v_add_f32_dpp v35, v35, v35 row_ror:8 row_mask:0xf bank_mask:0xf bound_ctrl:1
	s_waitcnt lgkmcnt(5)
	v_pk_mul_f32 v[36:37], v[114:115], v[34:35] op_sel_hi:[1,0]
	v_pk_mul_f32 v[38:39], v[116:117], v[34:35] op_sel_hi:[1,0]
	v_pk_fma_f32 v[36:37], v[122:123], v[130:131], v[36:37] op_sel_hi:[1,0,1] neg_lo:[0,0,1] neg_hi:[0,0,1]
	v_pk_fma_f32 v[38:39], v[124:125], v[130:131], v[38:39] op_sel_hi:[1,0,1] neg_lo:[0,0,1] neg_hi:[0,0,1]
	v_cndmask_b32_e64 v42, v42, v34, s[64:65]
	v_pk_fma_f32 v[28:29], v[28:29], v[118:119], v[36:37]
	v_pk_fma_f32 v[30:31], v[30:31], v[120:121], v[38:39]
	v_cndmask_b32_e64 v43, v43, v35, s[64:65]
	ds_read_b32 v154, v95 offset:16240
	s_waitcnt lgkmcnt(4)
	v_pk_mul_f32 v[24:25], v[30:31], v[136:137]
	v_pk_mul_f32 v[26:27], v[30:31], v[152:153]
	v_pk_fma_f32 v[24:25], v[28:29], v[134:135], v[24:25]
	v_pk_fma_f32 v[26:27], v[28:29], v[150:151], v[26:27]
	ds_read_b128 v[110:113], v94 offset:16320
	v_add_f32_e32 v34, v24, v25
	v_add_f32_e32 v35, v26, v27
	ds_read_b128 v[126:129], v94 offset:17344
	v_add_f32_dpp v34, v34, v34 quad_perm:[1,0,3,2] row_mask:0xf bank_mask:0xf bound_ctrl:1
	v_add_f32_dpp v35, v35, v35 quad_perm:[1,0,3,2] row_mask:0xf bank_mask:0xf bound_ctrl:1
	ds_read_b128 v[114:117], v94 offset:16576
	v_add_f32_dpp v34, v34, v34 quad_perm:[2,3,0,1] row_mask:0xf bank_mask:0xf bound_ctrl:1
	v_add_f32_dpp v35, v35, v35 quad_perm:[2,3,0,1] row_mask:0xf bank_mask:0xf bound_ctrl:1
	ds_read_b128 v[118:121], v94 offset:16832
	v_add_f32_dpp v34, v34, v34 row_ror:4 row_mask:0xf bank_mask:0xf bound_ctrl:1
	v_add_f32_dpp v35, v35, v35 row_ror:4 row_mask:0xf bank_mask:0xf bound_ctrl:1
	ds_read_b128 v[122:125], v94 offset:17088
	v_add_f32_dpp v34, v34, v34 row_ror:8 row_mask:0xf bank_mask:0xf bound_ctrl:1
	v_add_f32_dpp v35, v35, v35 row_ror:8 row_mask:0xf bank_mask:0xf bound_ctrl:1
	s_waitcnt lgkmcnt(5)
	v_pk_mul_f32 v[36:37], v[138:139], v[34:35] op_sel_hi:[1,0]
	v_pk_mul_f32 v[38:39], v[140:141], v[34:35] op_sel_hi:[1,0]
	v_pk_fma_f32 v[36:37], v[146:147], v[154:155], v[36:37] op_sel_hi:[1,0,1] neg_lo:[0,0,1] neg_hi:[0,0,1]
	v_pk_fma_f32 v[38:39], v[148:149], v[154:155], v[38:39] op_sel_hi:[1,0,1] neg_lo:[0,0,1] neg_hi:[0,0,1]
	v_cndmask_b32_e64 v42, v42, v34, s[66:67]
	v_pk_fma_f32 v[28:29], v[28:29], v[142:143], v[36:37]
	v_pk_fma_f32 v[30:31], v[30:31], v[144:145], v[38:39]
	v_cndmask_b32_e64 v43, v43, v35, s[66:67]
	ds_read_b32 v130, v95 offset:17600
	s_waitcnt lgkmcnt(4)
	v_pk_mul_f32 v[24:25], v[30:31], v[112:113]
	v_pk_mul_f32 v[26:27], v[30:31], v[128:129]
	v_pk_fma_f32 v[24:25], v[28:29], v[110:111], v[24:25]
	v_pk_fma_f32 v[26:27], v[28:29], v[126:127], v[26:27]
	ds_read_b128 v[134:137], v94 offset:17680
	v_add_f32_e32 v34, v24, v25
	v_add_f32_e32 v35, v26, v27
	ds_read_b128 v[150:153], v94 offset:18704
	v_add_f32_dpp v34, v34, v34 quad_perm:[1,0,3,2] row_mask:0xf bank_mask:0xf bound_ctrl:1
	v_add_f32_dpp v35, v35, v35 quad_perm:[1,0,3,2] row_mask:0xf bank_mask:0xf bound_ctrl:1
	ds_read_b128 v[138:141], v94 offset:17936
	v_add_f32_dpp v34, v34, v34 quad_perm:[2,3,0,1] row_mask:0xf bank_mask:0xf bound_ctrl:1
	v_add_f32_dpp v35, v35, v35 quad_perm:[2,3,0,1] row_mask:0xf bank_mask:0xf bound_ctrl:1
	ds_read_b128 v[142:145], v94 offset:18192
	v_add_f32_dpp v34, v34, v34 row_ror:4 row_mask:0xf bank_mask:0xf bound_ctrl:1
	v_add_f32_dpp v35, v35, v35 row_ror:4 row_mask:0xf bank_mask:0xf bound_ctrl:1
	ds_read_b128 v[146:149], v94 offset:18448
	v_add_f32_dpp v34, v34, v34 row_ror:8 row_mask:0xf bank_mask:0xf bound_ctrl:1
	v_add_f32_dpp v35, v35, v35 row_ror:8 row_mask:0xf bank_mask:0xf bound_ctrl:1
	s_waitcnt lgkmcnt(5)
	v_pk_mul_f32 v[36:37], v[114:115], v[34:35] op_sel_hi:[1,0]
	v_pk_mul_f32 v[38:39], v[116:117], v[34:35] op_sel_hi:[1,0]
	v_pk_fma_f32 v[36:37], v[122:123], v[130:131], v[36:37] op_sel_hi:[1,0,1] neg_lo:[0,0,1] neg_hi:[0,0,1]
	v_pk_fma_f32 v[38:39], v[124:125], v[130:131], v[38:39] op_sel_hi:[1,0,1] neg_lo:[0,0,1] neg_hi:[0,0,1]
	v_cndmask_b32_e64 v42, v42, v34, s[68:69]
	v_pk_fma_f32 v[28:29], v[28:29], v[118:119], v[36:37]
	v_pk_fma_f32 v[30:31], v[30:31], v[120:121], v[38:39]
	v_cndmask_b32_e64 v43, v43, v35, s[68:69]
	ds_read_b32 v154, v95 offset:18960
	s_waitcnt lgkmcnt(4)
	v_pk_mul_f32 v[24:25], v[30:31], v[136:137]
	v_pk_mul_f32 v[26:27], v[30:31], v[152:153]
	v_pk_fma_f32 v[24:25], v[28:29], v[134:135], v[24:25]
	v_pk_fma_f32 v[26:27], v[28:29], v[150:151], v[26:27]
	ds_read_b128 v[110:113], v94 offset:19040
	v_add_f32_e32 v34, v24, v25
	v_add_f32_e32 v35, v26, v27
	ds_read_b128 v[126:129], v94 offset:20064
	v_add_f32_dpp v34, v34, v34 quad_perm:[1,0,3,2] row_mask:0xf bank_mask:0xf bound_ctrl:1
	v_add_f32_dpp v35, v35, v35 quad_perm:[1,0,3,2] row_mask:0xf bank_mask:0xf bound_ctrl:1
	ds_read_b128 v[114:117], v94 offset:19296
	v_add_f32_dpp v34, v34, v34 quad_perm:[2,3,0,1] row_mask:0xf bank_mask:0xf bound_ctrl:1
	v_add_f32_dpp v35, v35, v35 quad_perm:[2,3,0,1] row_mask:0xf bank_mask:0xf bound_ctrl:1
	ds_read_b128 v[118:121], v94 offset:19552
	v_add_f32_dpp v34, v34, v34 row_ror:4 row_mask:0xf bank_mask:0xf bound_ctrl:1
	v_add_f32_dpp v35, v35, v35 row_ror:4 row_mask:0xf bank_mask:0xf bound_ctrl:1
	ds_read_b128 v[122:125], v94 offset:19808
	v_add_f32_dpp v34, v34, v34 row_ror:8 row_mask:0xf bank_mask:0xf bound_ctrl:1
	v_add_f32_dpp v35, v35, v35 row_ror:8 row_mask:0xf bank_mask:0xf bound_ctrl:1
	s_waitcnt lgkmcnt(5)
	v_pk_mul_f32 v[36:37], v[138:139], v[34:35] op_sel_hi:[1,0]
	v_pk_mul_f32 v[38:39], v[140:141], v[34:35] op_sel_hi:[1,0]
	v_pk_fma_f32 v[36:37], v[146:147], v[154:155], v[36:37] op_sel_hi:[1,0,1] neg_lo:[0,0,1] neg_hi:[0,0,1]
	v_pk_fma_f32 v[38:39], v[148:149], v[154:155], v[38:39] op_sel_hi:[1,0,1] neg_lo:[0,0,1] neg_hi:[0,0,1]
	v_cndmask_b32_e64 v42, v42, v34, s[76:77]
	v_pk_fma_f32 v[28:29], v[28:29], v[142:143], v[36:37]
	v_pk_fma_f32 v[30:31], v[30:31], v[144:145], v[38:39]
	v_cndmask_b32_e64 v43, v43, v35, s[76:77]
	ds_read_b32 v130, v95 offset:20320
	s_waitcnt lgkmcnt(4)
	v_pk_mul_f32 v[24:25], v[30:31], v[112:113]
	v_pk_mul_f32 v[26:27], v[30:31], v[128:129]
	v_pk_fma_f32 v[24:25], v[28:29], v[110:111], v[24:25]
	v_pk_fma_f32 v[26:27], v[28:29], v[126:127], v[26:27]
	ds_read_b128 v[134:137], v94 offset:20400
	v_add_f32_e32 v34, v24, v25
	v_add_f32_e32 v35, v26, v27
	ds_read_b128 v[150:153], v94 offset:21424
	v_add_f32_dpp v34, v34, v34 quad_perm:[1,0,3,2] row_mask:0xf bank_mask:0xf bound_ctrl:1
	v_add_f32_dpp v35, v35, v35 quad_perm:[1,0,3,2] row_mask:0xf bank_mask:0xf bound_ctrl:1
	ds_read_b128 v[138:141], v94 offset:20656
	v_add_f32_dpp v34, v34, v34 quad_perm:[2,3,0,1] row_mask:0xf bank_mask:0xf bound_ctrl:1
	v_add_f32_dpp v35, v35, v35 quad_perm:[2,3,0,1] row_mask:0xf bank_mask:0xf bound_ctrl:1
	ds_read_b128 v[142:145], v94 offset:20912
	v_add_f32_dpp v34, v34, v34 row_ror:4 row_mask:0xf bank_mask:0xf bound_ctrl:1
	v_add_f32_dpp v35, v35, v35 row_ror:4 row_mask:0xf bank_mask:0xf bound_ctrl:1
	ds_read_b128 v[146:149], v94 offset:21168
	v_add_f32_dpp v34, v34, v34 row_ror:8 row_mask:0xf bank_mask:0xf bound_ctrl:1
	v_add_f32_dpp v35, v35, v35 row_ror:8 row_mask:0xf bank_mask:0xf bound_ctrl:1
	s_waitcnt lgkmcnt(5)
	v_pk_mul_f32 v[36:37], v[114:115], v[34:35] op_sel_hi:[1,0]
	v_pk_mul_f32 v[38:39], v[116:117], v[34:35] op_sel_hi:[1,0]
	v_pk_fma_f32 v[36:37], v[122:123], v[130:131], v[36:37] op_sel_hi:[1,0,1] neg_lo:[0,0,1] neg_hi:[0,0,1]
	v_pk_fma_f32 v[38:39], v[124:125], v[130:131], v[38:39] op_sel_hi:[1,0,1] neg_lo:[0,0,1] neg_hi:[0,0,1]
	v_cndmask_b32_e32 v42, v42, v34, vcc
	v_pk_fma_f32 v[28:29], v[28:29], v[118:119], v[36:37]
	v_pk_fma_f32 v[30:31], v[30:31], v[120:121], v[38:39]
	v_cndmask_b32_e32 v43, v43, v35, vcc
	ds_read_b32 v154, v95 offset:21680
	s_waitcnt lgkmcnt(4)
	v_pk_mul_f32 v[24:25], v[30:31], v[136:137]
	v_pk_mul_f32 v[26:27], v[30:31], v[152:153]
	v_pk_fma_f32 v[24:25], v[28:29], v[134:135], v[24:25]
	v_pk_fma_f32 v[26:27], v[28:29], v[150:151], v[26:27]
	v_add_f32_e32 v34, v24, v25
	v_add_f32_e32 v35, v26, v27
	v_lshl_add_u64 v[70:71], v[70:71], 0, s[2:3]
	v_add_f32_dpp v34, v34, v34 quad_perm:[1,0,3,2] row_mask:0xf bank_mask:0xf bound_ctrl:1
	v_add_f32_dpp v35, v35, v35 quad_perm:[1,0,3,2] row_mask:0xf bank_mask:0xf bound_ctrl:1
	v_lshl_add_u64 v[72:73], v[72:73], 0, s[20:21]
	v_add_f32_dpp v34, v34, v34 quad_perm:[2,3,0,1] row_mask:0xf bank_mask:0xf bound_ctrl:1
	v_add_f32_dpp v35, v35, v35 quad_perm:[2,3,0,1] row_mask:0xf bank_mask:0xf bound_ctrl:1
	v_lshl_add_u64 v[74:75], v[74:75], 0, s[20:21]
	v_add_f32_dpp v34, v34, v34 row_ror:4 row_mask:0xf bank_mask:0xf bound_ctrl:1
	v_add_f32_dpp v35, v35, v35 row_ror:4 row_mask:0xf bank_mask:0xf bound_ctrl:1
	s_nop 0
	v_add_f32_dpp v34, v34, v34 row_ror:8 row_mask:0xf bank_mask:0xf bound_ctrl:1
	v_add_f32_dpp v35, v35, v35 row_ror:8 row_mask:0xf bank_mask:0xf bound_ctrl:1
	s_waitcnt lgkmcnt(0)
	v_pk_mul_f32 v[36:37], v[138:139], v[34:35] op_sel_hi:[1,0]
	v_pk_mul_f32 v[38:39], v[140:141], v[34:35] op_sel_hi:[1,0]
	v_pk_fma_f32 v[36:37], v[146:147], v[154:155], v[36:37] op_sel_hi:[1,0,1] neg_lo:[0,0,1] neg_hi:[0,0,1]
	v_pk_fma_f32 v[38:39], v[148:149], v[154:155], v[38:39] op_sel_hi:[1,0,1] neg_lo:[0,0,1] neg_hi:[0,0,1]
	v_cndmask_b32_e64 v42, v42, v34, s[4:5]
	v_pk_fma_f32 v[28:29], v[28:29], v[142:143], v[36:37]
	v_pk_fma_f32 v[30:31], v[30:31], v[144:145], v[38:39]
	v_cndmask_b32_e64 v43, v43, v35, s[4:5]
	v_lshl_add_u64 v[24:25], v[68:69], 0, s[0:1]
	s_add_u32 s0, s0, 0x1000
	s_addc_u32 s1, s1, 0
	s_mov_b32 s24, s38
	v_fma_f32 v40, -v44, v42, v43
	s_cmp_lg_u32 s0, 0x54000
	v_fmac_f32_e32 v40, v48, v45
	global_store_dword v[24:25], v40, off
	s_barrier
	s_cbranch_scc0 .LBB0_233
